# w_down transposes in the P1 K-loop: one dwordx2 load per iteration into a rotating 32-register window, full-line stores in the tile epilogue; peel; epilogue prefetch
# speedup vs baseline: 1.0062x; 1.0010x over previous
;     __device__ __forceinline__ unsigned voffA(int R, int C) const { return (unsigned)(R * lda + C) * 2u; }
;     __device__ __forceinline__ unsigned voffB(int R, int C) const { return (unsigned)(R * ldb + C) * 2u; }
;     __device__ __forceinline__ unsigned voffA(int R, int C) const { return (unsigned)(R * 256 + C) * 2u; }
;     __device__ __forceinline__ unsigned voffB(int R, int C) const { return (unsigned)((256 * (R & 15) + (R >> 4)) * 1024 + C) * 2u; }
;     __device__ __forceinline__ unsigned voffA(int R, int C) const { return (unsigned)(R * 512 + C) * 2u; }
;     __device__ __forceinline__ unsigned voffB(int R, int C) const { return (unsigned)(R * 8192 + C) * 2u; }
; #define PG8_STAGE(bufoff, gbase, voff) do { _Pragma("unroll") for (int _i = 0; _i < 2; ++_i) { const unsigned _vo = (voff)[_i]; \
;         __builtin_amdgcn_global_load_lds((const PG8_GAS unsigned*)((const PG8_GAS char*)(gbase) + _vo), (PG8_LAS unsigned*)(lds + (bufoff) + ldsw + _i * 8192), 16, 0, 0); } } while (0)
; #define PG8_WAIT_V(n) asm volatile("s_waitcnt vmcnt(" #n ")" ::: "memory")
; #define PG8_BAR __builtin_amdgcn_s_barrier()
;     ...
;     const unsigned ldsw = (unsigned)wid * 1024u;
;     const int aoff = lds_byte(wr * 64 + fr, fq * 8), boff = lds_byte(wc * 32 + fr, fq * 8);
;     ...
;     PG8_STAGE(PG8_SB(0, 0), cB, voffB); PG8_STAGE(PG8_SB(0, 1), cB + hstepB, voffB); PG8_STAGE(PG8_SA(0, 0), cA, voffA); PG8_STAGE(PG8_SA(0, 1), cA + hstepA, voffA);
;     if (wr == 1) PG8_BAR;
;     PG8_WAIT_V(2); PG8_BAR;
;     PG8_STAGE(PG8_SB(1, 0), cB + kstep, voffB); PG8_STAGE(PG8_SA(1, 0), cA + kstep, voffA); PG8_STAGE(PG8_SB(1, 1), cB + hstepB + kstep, voffB);
;     PG8_WAIT_V(6); PG8_BAR;
.LBB0_172:
	s_add_u32 s12, s94, 0x100000
	s_mov_b64 s[8:9], 0x80
	s_addc_u32 s13, s95, 0
	s_add_i32 m0, s38, 0x18000
	v_lshl_add_u64 v[4:5], v[4:5], 0, s[8:9]
	s_waitcnt vmcnt(2)
	s_barrier
	global_load_lds_dwordx4 v[4:5], off
	v_lshl_add_u64 v[2:3], v[2:3], 0, s[8:9]
	s_add_i32 m0, s38, 0x1a000
	s_add_i32 s14, s38, 0x8000
	global_load_lds_dwordx4 v[2:3], off
	v_lshl_add_u64 v[0:1], v[0:1], 0, s[8:9]
	s_mov_b32 m0, s14
	s_add_i32 s15, s38, 0xa000
	global_load_lds_dwordx4 v[0:1], off
	v_lshl_add_u64 v[0:1], v[6:7], 0, s[8:9]
	s_add_u32 s8, s30, 0x80080
	s_mov_b32 m0, s15
	s_addc_u32 s9, s31, 0
	global_load_lds_dwordx4 v[0:1], off
	s_add_i32 m0, s38, 0x1c000
	v_lshl_add_u64 v[0:1], s[8:9], 0, v[130:131]
	global_load_lds_dwordx4 v[0:1], off
	v_lshl_add_u64 v[0:1], s[8:9], 0, v[134:135]
	s_add_i32 m0, s38, 0x1e000
	v_and_b32_e32 v4, 48, v8
	global_load_lds_dwordx4 v[0:1], off
	v_and_b32_e32 v0, 15, v8
	v_or_b32_e32 v1, s48, v0
	v_lshlrev_b32_e32 v3, 6, v1
	s_movk_i32 s5, 0x3c0
	v_ashrrev_i32_e32 v2, 6, v8
	v_and_or_b32 v3, v3, s5, v4
	v_readlane_b32 s5, v254, 18
	v_lshlrev_b32_e32 v1, 2, v1
	v_and_b32_e32 v1, 32, v1
	v_lshl_add_u32 v5, v2, 10, s5
	v_readlane_b32 s5, v254, 19
	v_bitop3_b32 v1, v3, v5, v1 bitop3:0xde
	v_lshlrev_b32_e32 v3, 2, v8
	v_add_lshl_u32 v2, v2, s5, 10
	v_readlane_b32 s5, v254, 14
	v_lshl_or_b32 v0, v0, 6, v4
	v_and_b32_e32 v3, 32, v3
	s_waitcnt vmcnt(6)
	s_cmpk_lt_u32 s5, 0x100
	v_bitop3_b32 v129, v0, v2, v3 bitop3:0xde
	s_cselect_b64 s[16:17], -1, 0
	s_add_i32 s57, 0, 0x10000
	s_add_i32 s60, 0, 0x14000
	s_ashr_i32 s55, s3, 31
	s_ashr_i32 s56, s2, 31
	v_mov_b64_e32 v[136:137], 0x400
	v_mov_b64_e32 v[138:139], 0x3ff
	v_add_u32_e32 v133, s57, v129
	v_add_u32_e32 v135, s60, v129
	v_add_u32_e32 v164, 0, v1
	v_mov_b32_e32 v165, 0x3e0293ee
	v_mov_b32_e32 v166, v130
	s_barrier
	v_lshrrev_b32_e32 v250, 4, v8
	v_and_b32_e32 v251, 15, v8
	v_lshlrev_b32_e32 v250, 17, v250
	v_lshl_or_b32 v250, v251, 3, v250
	v_readlane_b32 s98, v254, 0
	v_readlane_b32 s99, v254, 1
	s_sub_u32 s98, s98, 0x58
	s_subb_u32 s99, s99, 0
	s_load_dwordx2 s[100:101], s[98:99], 0x38
	s_waitcnt lgkmcnt(0)
	v_writelane_b32 v252, s100, 0
	v_writelane_b32 v252, s101, 1
	s_add_u32 s98, s94, 0x4400000
	s_addc_u32 s99, s95, 0
	v_writelane_b32 v252, s98, 2
	v_writelane_b32 v252, s99, 3
	s_lshl_b32 s98, s2, 3
	s_add_i32 s98, s98, s49
	s_and_b32 s98, s98, 0x7ff
	v_writelane_b32 v252, s98, 5
	s_branch .LBB0_175

;     __device__ __forceinline__ const char* a(const Unit& u) const { return (const char*)A + (size_t)u.pm * 2 * hA(); }
;     __device__ __forceinline__ const char* b(const Unit& u) const { return (const char*)Bt + (size_t)u.pn * 2 * hB() + (size_t)(u.pm >> gshift) * goff; }
;     __device__ __forceinline__ const char* a(const Unit& u) const { return (const char*)A + (size_t)u.pm * 2 * hA(); }
;     __device__ __forceinline__ const char* b(const Unit& u) const { return (const char*)Bt + (size_t)((u.pn >> 4) * 4096 + (u.pn & 15) * 16) * 1024 * 2 + (size_t)(u.pm >> 1) * 512; }
;     __device__ __forceinline__ const char* a(const Unit&) const { return (const char*)A; }
;     __device__ __forceinline__ const char* b(const Unit& u) const { return (const char*)Bt + ((size_t)(((u.pm >> 4) * 1024 + u.pn * 256) * 16 + (u.pm & 15)) * 512) * 2; }
;     ...
; #pragma unroll
;         for (int a = 0; a < 2; ++a)
; #pragma unroll
;             for (int b = 0; b < 2; ++b)
; #pragma unroll
;                 for (int m = 0; m < 4; ++m)
; #pragma unroll
;                     for (int n = 0; n < 2; ++n) acc[a][b][m][n] = (f32x4){0.f, 0.f, 0.f, 0.f};
;         cur = nxt; cA = nA; cB = nB; ++ui;
.LBB0_181:
	s_ashr_i32 s21, s20, 31
	s_lshl_b64 s[22:23], s[20:21], 20
	v_readlane_b32 s26, v254, 20
	v_readlane_b32 s27, v254, 21
	s_add_u32 s22, s26, s22
	s_addc_u32 s23, s27, s23
	s_and_b64 s[26:27], s[8:9], exec
	s_cselect_b32 s5, s23, s29
	s_cselect_b32 s7, s22, s28
	s_ashr_i32 s19, s18, 31
	s_lshl_b64 s[26:27], s[18:19], 20
	s_add_u32 s26, s24, s26
	s_addc_u32 s27, s25, s27
	s_and_b64 s[34:35], s[8:9], exec
	s_cselect_b32 s19, s27, s31
	s_cselect_b32 s21, s26, s30
	s_add_u32 s61, s30, 0x100
	v_mov_b32_e32 v0, 0
	s_addc_u32 s66, s31, 0
	s_mov_b32 s67, -2
	v_mov_b32_e32 v1, v0
	v_mov_b32_e32 v2, v0
	v_mov_b32_e32 v3, v0
	v_mov_b32_e32 v4, v0
	v_mov_b32_e32 v5, v0
	v_mov_b32_e32 v6, v0
	v_mov_b32_e32 v7, v0
	v_mov_b32_e32 v16, v0
	v_mov_b32_e32 v17, v0
	v_mov_b32_e32 v18, v0
	v_mov_b32_e32 v19, v0
	v_mov_b32_e32 v20, v0
	v_mov_b32_e32 v21, v0
	v_mov_b32_e32 v22, v0
	v_mov_b32_e32 v23, v0
	v_mov_b32_e32 v32, v0
	v_mov_b32_e32 v33, v0
	v_mov_b32_e32 v34, v0
	v_mov_b32_e32 v35, v0
	v_mov_b32_e32 v36, v0
	v_mov_b32_e32 v37, v0
	v_mov_b32_e32 v38, v0
	v_mov_b32_e32 v39, v0
	v_mov_b32_e32 v48, v0
	v_mov_b32_e32 v49, v0
	v_mov_b32_e32 v50, v0
	v_mov_b32_e32 v51, v0
	v_mov_b32_e32 v52, v0
	v_mov_b32_e32 v53, v0
	v_mov_b32_e32 v54, v0
	v_mov_b32_e32 v55, v0
	v_mov_b32_e32 v8, v0
	v_mov_b32_e32 v9, v0
	v_mov_b32_e32 v10, v0
	v_mov_b32_e32 v11, v0
	v_mov_b32_e32 v12, v0
	v_mov_b32_e32 v13, v0
	v_mov_b32_e32 v14, v0
	v_mov_b32_e32 v15, v0
	v_mov_b32_e32 v24, v0
	v_mov_b32_e32 v25, v0
	v_mov_b32_e32 v26, v0
	v_mov_b32_e32 v27, v0
	v_mov_b32_e32 v28, v0
	v_mov_b32_e32 v29, v0
	v_mov_b32_e32 v30, v0
	v_mov_b32_e32 v31, v0
	v_mov_b32_e32 v40, v0
	v_mov_b32_e32 v41, v0
	v_mov_b32_e32 v42, v0
	v_mov_b32_e32 v43, v0
	v_mov_b32_e32 v44, v0
	v_mov_b32_e32 v45, v0
	v_mov_b32_e32 v46, v0
	v_mov_b32_e32 v47, v0
	v_mov_b32_e32 v56, v0
	v_mov_b32_e32 v57, v0
	v_mov_b32_e32 v58, v0
	v_mov_b32_e32 v59, v0
	v_mov_b32_e32 v60, v0
	v_mov_b32_e32 v61, v0
	v_mov_b32_e32 v62, v0
	v_mov_b32_e32 v63, v0
	v_mov_b32_e32 v64, v0
	v_mov_b32_e32 v65, v0
	v_mov_b32_e32 v66, v0
	v_mov_b32_e32 v67, v0
	v_mov_b32_e32 v68, v0
	v_mov_b32_e32 v69, v0
	v_mov_b32_e32 v70, v0
	v_mov_b32_e32 v71, v0
	v_mov_b32_e32 v80, v0
	v_mov_b32_e32 v81, v0
	v_mov_b32_e32 v82, v0
	v_mov_b32_e32 v83, v0
	v_mov_b32_e32 v84, v0
	v_mov_b32_e32 v85, v0
	v_mov_b32_e32 v86, v0
	v_mov_b32_e32 v87, v0
	v_mov_b32_e32 v96, v0
	v_mov_b32_e32 v97, v0
	v_mov_b32_e32 v98, v0
	v_mov_b32_e32 v99, v0
	v_mov_b32_e32 v100, v0
	v_mov_b32_e32 v101, v0
	v_mov_b32_e32 v102, v0
	v_mov_b32_e32 v103, v0
	v_mov_b32_e32 v112, v0
	v_mov_b32_e32 v113, v0
	v_mov_b32_e32 v114, v0
	v_mov_b32_e32 v115, v0
	v_mov_b32_e32 v116, v0
	v_mov_b32_e32 v117, v0
	v_mov_b32_e32 v118, v0
	v_mov_b32_e32 v119, v0
	v_mov_b32_e32 v72, v0
	v_mov_b32_e32 v73, v0
	v_mov_b32_e32 v74, v0
	v_mov_b32_e32 v75, v0
	v_mov_b32_e32 v76, v0
	v_mov_b32_e32 v77, v0
	v_mov_b32_e32 v78, v0
	v_mov_b32_e32 v79, v0
	v_mov_b32_e32 v88, v0
	v_mov_b32_e32 v89, v0
	v_mov_b32_e32 v90, v0
	v_mov_b32_e32 v91, v0
	v_mov_b32_e32 v92, v0
	v_mov_b32_e32 v93, v0
	v_mov_b32_e32 v94, v0
	v_mov_b32_e32 v95, v0
	v_mov_b32_e32 v104, v0
	v_mov_b32_e32 v105, v0
	v_mov_b32_e32 v106, v0
	v_mov_b32_e32 v107, v0
	v_mov_b32_e32 v108, v0
	v_mov_b32_e32 v109, v0
	v_mov_b32_e32 v110, v0
	v_mov_b32_e32 v111, v0
	v_mov_b32_e32 v120, v0
	v_mov_b32_e32 v121, v0
	v_mov_b32_e32 v122, v0
	v_mov_b32_e32 v123, v0
	v_mov_b32_e32 v124, v0
	v_mov_b32_e32 v125, v0
	v_mov_b32_e32 v126, v0
	v_mov_b32_e32 v127, v0
	v_readlane_b32 s98, v252, 5
	s_sub_i32 s99, s54, 1
	s_lshl_b32 s99, s99, 11
	s_add_i32 s98, s98, s99
	s_and_b32 s98, s98, 0x1fff
	s_lshr_b32 s99, s98, 6
	s_and_b32 s98, s98, 63
	s_lshl_b32 s99, s99, 19
	s_lshl_b32 s98, s98, 7
	s_add_u32 s98, s98, s99
	v_readlane_b32 s100, v252, 0
	v_readlane_b32 s101, v252, 1
	s_add_u32 s98, s100, s98
	s_addc_u32 s99, s101, 0
	s_cmp_lt_u32 s54, 2
	s_cbranch_scc1 .LBB0_182
	s_add_u32 s30, s28, 0x100
	s_addc_u32 s31, s29, 0
	s_cmp_eq_u32 s67, 28
	s_cselect_b32 s42, s7, s30
	s_cselect_b32 s43, s5, s31
	s_cselect_b32 s45, s19, s66
	s_cselect_b32 s44, s21, s61
	s_add_u32 s34, s42, 0x80
	s_addc_u32 s35, s43, 0
	s_add_u32 s36, s44, 0x80
	s_addc_u32 s37, s45, 0
	s_add_u32 s68, s28, 0x80080
	s_addc_u32 s69, s29, 0
	s_add_u32 s40, s42, 0x80000
	s_addc_u32 s41, s43, 0
	s_add_u32 s46, s44, 0x80000
	s_addc_u32 s47, s45, 0
	s_add_u32 s28, s44, 0x80080
	s_addc_u32 s29, s45, 0
	ds_read_b128 v[140:143], v133
	ds_read_b128 v[144:147], v133 offset:1024
	ds_read_b128 v[148:151], v133 offset:2048
	ds_read_b128 v[152:155], v133 offset:3072
	ds_read_b128 v[156:159], v135
	ds_read_b128 v[160:163], v135 offset:1024
	ds_read_b128 v[168:171], v135 offset:2048
	ds_read_b128 v[172:175], v135 offset:3072
	s_add_i32 m0, s38, 0xc000
	ds_read_b128 v[176:179], v164
	ds_read_b128 v[180:183], v164 offset:1024
	ds_read_b128 v[184:187], v164 offset:2048
	ds_read_b128 v[188:191], v164 offset:3072
	ds_read_b128 v[192:195], v164 offset:4096
	ds_read_b128 v[196:199], v164 offset:5120
	ds_read_b128 v[200:203], v164 offset:6144
	ds_read_b128 v[204:207], v164 offset:7168
	global_load_lds_dwordx4 v128, s[68:69]
	s_add_i32 m0, s38, 0xe000
	s_nop 0
	global_load_lds_dwordx4 v132, s[68:69]
	s_waitcnt vmcnt(36)
	s_waitcnt lgkmcnt(0)
	s_barrier
	s_setprio 1
	s_waitcnt lgkmcnt(0)
	v_mfma_f32_16x16x32_bf16 v[124:127], v[140:143], v[176:179], v[124:127]
	v_mov_b32_e32 v208, v210
	v_mfma_f32_16x16x32_bf16 v[120:123], v[148:151], v[176:179], v[120:123]
	v_mov_b32_e32 v209, v211
	v_mfma_f32_16x16x32_bf16 v[108:111], v[140:143], v[184:187], v[108:111]
	v_mov_b32_e32 v210, v212
	v_mfma_f32_16x16x32_bf16 v[104:107], v[148:151], v[184:187], v[104:107]
	v_mov_b32_e32 v211, v213
	v_mfma_f32_16x16x32_bf16 v[92:95], v[140:143], v[192:195], v[92:95]
	v_mov_b32_e32 v212, v214
	v_mfma_f32_16x16x32_bf16 v[88:91], v[148:151], v[192:195], v[88:91]
	v_mov_b32_e32 v213, v215
	v_mfma_f32_16x16x32_bf16 v[76:79], v[140:143], v[200:203], v[76:79]
	v_mov_b32_e32 v214, v216
	v_mfma_f32_16x16x32_bf16 v[72:75], v[148:151], v[200:203], v[72:75]
	v_mov_b32_e32 v215, v217
	v_mfma_f32_16x16x32_bf16 v[124:127], v[144:147], v[180:183], v[124:127]
	v_mov_b32_e32 v216, v218
	v_mfma_f32_16x16x32_bf16 v[120:123], v[152:155], v[180:183], v[120:123]
	v_mov_b32_e32 v217, v219
	v_mfma_f32_16x16x32_bf16 v[108:111], v[144:147], v[188:191], v[108:111]
	v_mov_b32_e32 v218, v220
	v_mfma_f32_16x16x32_bf16 v[104:107], v[152:155], v[188:191], v[104:107]
	v_mov_b32_e32 v219, v221
	v_mfma_f32_16x16x32_bf16 v[92:95], v[144:147], v[196:199], v[92:95]
	v_mov_b32_e32 v220, v222
	v_mfma_f32_16x16x32_bf16 v[88:91], v[152:155], v[196:199], v[88:91]
	v_mov_b32_e32 v221, v223
	v_mfma_f32_16x16x32_bf16 v[76:79], v[144:147], v[204:207], v[76:79]
	v_mov_b32_e32 v222, v224
	v_mfma_f32_16x16x32_bf16 v[72:75], v[152:155], v[204:207], v[72:75]
	v_mov_b32_e32 v223, v225
	s_setprio 0
	s_setprio 1
	v_mfma_f32_16x16x32_bf16 v[116:119], v[156:159], v[176:179], v[116:119]
	v_mov_b32_e32 v224, v226
	v_mfma_f32_16x16x32_bf16 v[112:115], v[168:171], v[176:179], v[112:115]
	v_mov_b32_e32 v225, v227
	v_mfma_f32_16x16x32_bf16 v[100:103], v[156:159], v[184:187], v[100:103]
	v_mov_b32_e32 v226, v228
	v_mfma_f32_16x16x32_bf16 v[96:99], v[168:171], v[184:187], v[96:99]
	v_mov_b32_e32 v227, v229
	v_mfma_f32_16x16x32_bf16 v[84:87], v[156:159], v[192:195], v[84:87]
	v_mov_b32_e32 v228, v230
	v_mfma_f32_16x16x32_bf16 v[80:83], v[168:171], v[192:195], v[80:83]
	v_mov_b32_e32 v229, v231
	v_mfma_f32_16x16x32_bf16 v[68:71], v[156:159], v[200:203], v[68:71]
	v_mov_b32_e32 v230, v232
	v_mfma_f32_16x16x32_bf16 v[64:67], v[168:171], v[200:203], v[64:67]
	v_mov_b32_e32 v231, v233
	v_mfma_f32_16x16x32_bf16 v[116:119], v[160:163], v[180:183], v[116:119]
	v_mov_b32_e32 v232, v234
	v_mfma_f32_16x16x32_bf16 v[112:115], v[172:175], v[180:183], v[112:115]
	v_mov_b32_e32 v233, v235
	v_mfma_f32_16x16x32_bf16 v[100:103], v[160:163], v[188:191], v[100:103]
	v_mov_b32_e32 v234, v236
	v_mfma_f32_16x16x32_bf16 v[96:99], v[172:175], v[188:191], v[96:99]
	v_mov_b32_e32 v235, v237
	v_mfma_f32_16x16x32_bf16 v[84:87], v[160:163], v[196:199], v[84:87]
	v_mov_b32_e32 v236, v238
	v_mfma_f32_16x16x32_bf16 v[80:83], v[172:175], v[196:199], v[80:83]
	v_mov_b32_e32 v237, v239
	v_mfma_f32_16x16x32_bf16 v[68:71], v[160:163], v[204:207], v[68:71]
	v_mfma_f32_16x16x32_bf16 v[64:67], v[172:175], v[204:207], v[64:67]
	s_setprio 0
	s_barrier
	s_add_i32 s68, s57, s33
	s_mov_b32 m0, s68
	ds_read_b128 v[176:179], v164 offset:16384
	ds_read_b128 v[180:183], v164 offset:17408
	ds_read_b128 v[184:187], v164 offset:18432
	ds_read_b128 v[188:191], v164 offset:19456
	ds_read_b128 v[192:195], v164 offset:20480
	ds_read_b128 v[196:199], v164 offset:21504
	ds_read_b128 v[200:203], v164 offset:22528
	ds_read_b128 v[204:207], v164 offset:23552
	global_load_lds_dwordx4 v166, s[44:45]
	s_add_i32 m0, s68, 0x2000
	s_nop 0
	global_load_lds_dwordx4 v134, s[44:45]
	s_add_i32 s44, s60, s33
	s_mov_b32 m0, s44
	s_nop 0
	global_load_lds_dwordx4 v166, s[46:47]
	s_add_i32 m0, s44, 0x2000
	s_nop 0
	global_load_lds_dwordx4 v134, s[46:47]
	s_mov_b32 m0, s38
	s_nop 0
	global_load_lds_dwordx4 v128, s[42:43]
	s_mov_b32 m0, s39
	s_nop 0
	global_load_lds_dwordx4 v132, s[42:43]
	global_load_dwordx2 v[238:239], v250, s[98:99] nt
	s_add_u32 s98, s98, 0x2000
	s_addc_u32 s99, s99, 0
	s_waitcnt vmcnt(37)
	s_waitcnt lgkmcnt(0)
	s_barrier
	s_setprio 1
	s_waitcnt lgkmcnt(0)
	v_mfma_f32_16x16x32_bf16 v[60:63], v[140:143], v[176:179], v[60:63]
	v_mfma_f32_16x16x32_bf16 v[56:59], v[148:151], v[176:179], v[56:59]
	v_mfma_f32_16x16x32_bf16 v[44:47], v[140:143], v[184:187], v[44:47]
	v_mfma_f32_16x16x32_bf16 v[40:43], v[148:151], v[184:187], v[40:43]
	v_mfma_f32_16x16x32_bf16 v[28:31], v[140:143], v[192:195], v[28:31]
	v_mfma_f32_16x16x32_bf16 v[24:27], v[148:151], v[192:195], v[24:27]
	v_mfma_f32_16x16x32_bf16 v[12:15], v[140:143], v[200:203], v[12:15]
	v_mfma_f32_16x16x32_bf16 v[8:11], v[148:151], v[200:203], v[8:11]
	v_mfma_f32_16x16x32_bf16 v[60:63], v[144:147], v[180:183], v[60:63]
	v_mfma_f32_16x16x32_bf16 v[56:59], v[152:155], v[180:183], v[56:59]
	v_mfma_f32_16x16x32_bf16 v[44:47], v[144:147], v[188:191], v[44:47]
	v_mfma_f32_16x16x32_bf16 v[40:43], v[152:155], v[188:191], v[40:43]
	v_mfma_f32_16x16x32_bf16 v[28:31], v[144:147], v[196:199], v[28:31]
	v_mfma_f32_16x16x32_bf16 v[24:27], v[152:155], v[196:199], v[24:27]
	v_mfma_f32_16x16x32_bf16 v[12:15], v[144:147], v[204:207], v[12:15]
	v_mfma_f32_16x16x32_bf16 v[8:11], v[152:155], v[204:207], v[8:11]
	s_setprio 0
	s_setprio 1
	v_mfma_f32_16x16x32_bf16 v[52:55], v[156:159], v[176:179], v[52:55]
	v_mfma_f32_16x16x32_bf16 v[48:51], v[168:171], v[176:179], v[48:51]
	v_mfma_f32_16x16x32_bf16 v[36:39], v[156:159], v[184:187], v[36:39]
	v_mfma_f32_16x16x32_bf16 v[32:35], v[168:171], v[184:187], v[32:35]
	v_mfma_f32_16x16x32_bf16 v[20:23], v[156:159], v[192:195], v[20:23]
	v_mfma_f32_16x16x32_bf16 v[16:19], v[168:171], v[192:195], v[16:19]
	v_mfma_f32_16x16x32_bf16 v[4:7], v[156:159], v[200:203], v[4:7]
	v_mfma_f32_16x16x32_bf16 v[0:3], v[168:171], v[200:203], v[0:3]
	v_mfma_f32_16x16x32_bf16 v[52:55], v[160:163], v[180:183], v[52:55]
	v_mfma_f32_16x16x32_bf16 v[48:51], v[172:175], v[180:183], v[48:51]
	v_mfma_f32_16x16x32_bf16 v[36:39], v[160:163], v[188:191], v[36:39]
	v_mfma_f32_16x16x32_bf16 v[32:35], v[172:175], v[188:191], v[32:35]
	v_mfma_f32_16x16x32_bf16 v[20:23], v[160:163], v[196:199], v[20:23]
	v_mfma_f32_16x16x32_bf16 v[16:19], v[172:175], v[196:199], v[16:19]
	v_mfma_f32_16x16x32_bf16 v[4:7], v[160:163], v[204:207], v[4:7]
	v_mfma_f32_16x16x32_bf16 v[0:3], v[172:175], v[204:207], v[0:3]
	s_setprio 0
	s_barrier
	s_add_i32 s42, 0, 0x18000
	v_add_u32_e32 v130, s42, v129
	s_add_i32 s43, 0, 0x1c000
	ds_read_b128 v[140:143], v130
	ds_read_b128 v[144:147], v130 offset:1024
	ds_read_b128 v[148:151], v130 offset:2048
	ds_read_b128 v[152:155], v130 offset:3072
	v_add_u32_e32 v130, s43, v129
	ds_read_b128 v[156:159], v130
	ds_read_b128 v[160:163], v130 offset:1024
	ds_read_b128 v[168:171], v130 offset:2048
	ds_read_b128 v[172:175], v130 offset:3072
	s_mov_b32 m0, s52
	ds_read_b128 v[176:179], v164 offset:32768
	ds_read_b128 v[180:183], v164 offset:33792
	ds_read_b128 v[184:187], v164 offset:34816
	ds_read_b128 v[188:191], v164 offset:35840
	ds_read_b128 v[192:195], v164 offset:36864
	ds_read_b128 v[196:199], v164 offset:37888
	ds_read_b128 v[200:203], v164 offset:38912
	ds_read_b128 v[204:207], v164 offset:39936
	global_load_lds_dwordx4 v128, s[40:41]
	s_mov_b32 m0, s53
	s_nop 0
	global_load_lds_dwordx4 v132, s[40:41]
	s_waitcnt vmcnt(9)
	s_waitcnt lgkmcnt(0)
	s_barrier
	s_setprio 1
	s_waitcnt lgkmcnt(0)
	v_mfma_f32_16x16x32_bf16 v[124:127], v[140:143], v[176:179], v[124:127]
	v_mfma_f32_16x16x32_bf16 v[120:123], v[148:151], v[176:179], v[120:123]
	v_mfma_f32_16x16x32_bf16 v[108:111], v[140:143], v[184:187], v[108:111]
	v_mfma_f32_16x16x32_bf16 v[104:107], v[148:151], v[184:187], v[104:107]
	v_mfma_f32_16x16x32_bf16 v[92:95], v[140:143], v[192:195], v[92:95]
	v_mfma_f32_16x16x32_bf16 v[88:91], v[148:151], v[192:195], v[88:91]
	v_mfma_f32_16x16x32_bf16 v[76:79], v[140:143], v[200:203], v[76:79]
	v_mfma_f32_16x16x32_bf16 v[72:75], v[148:151], v[200:203], v[72:75]
	v_mfma_f32_16x16x32_bf16 v[124:127], v[144:147], v[180:183], v[124:127]
	v_mfma_f32_16x16x32_bf16 v[120:123], v[152:155], v[180:183], v[120:123]
	v_mfma_f32_16x16x32_bf16 v[108:111], v[144:147], v[188:191], v[108:111]
	v_mfma_f32_16x16x32_bf16 v[104:107], v[152:155], v[188:191], v[104:107]
	v_mfma_f32_16x16x32_bf16 v[92:95], v[144:147], v[196:199], v[92:95]
	v_mfma_f32_16x16x32_bf16 v[88:91], v[152:155], v[196:199], v[88:91]
	v_mfma_f32_16x16x32_bf16 v[76:79], v[144:147], v[204:207], v[76:79]
	v_mfma_f32_16x16x32_bf16 v[72:75], v[152:155], v[204:207], v[72:75]
	s_setprio 0
	s_setprio 1
	v_mfma_f32_16x16x32_bf16 v[116:119], v[156:159], v[176:179], v[116:119]
	v_mfma_f32_16x16x32_bf16 v[112:115], v[168:171], v[176:179], v[112:115]
	v_mfma_f32_16x16x32_bf16 v[100:103], v[156:159], v[184:187], v[100:103]
	v_mfma_f32_16x16x32_bf16 v[96:99], v[168:171], v[184:187], v[96:99]
	v_mfma_f32_16x16x32_bf16 v[84:87], v[156:159], v[192:195], v[84:87]
	v_mfma_f32_16x16x32_bf16 v[80:83], v[168:171], v[192:195], v[80:83]
	v_mfma_f32_16x16x32_bf16 v[68:71], v[156:159], v[200:203], v[68:71]
	v_mfma_f32_16x16x32_bf16 v[64:67], v[168:171], v[200:203], v[64:67]
	v_mfma_f32_16x16x32_bf16 v[116:119], v[160:163], v[180:183], v[116:119]
	v_mfma_f32_16x16x32_bf16 v[112:115], v[172:175], v[180:183], v[112:115]
	v_mfma_f32_16x16x32_bf16 v[100:103], v[160:163], v[188:191], v[100:103]
	v_mfma_f32_16x16x32_bf16 v[96:99], v[172:175], v[188:191], v[96:99]
	v_mfma_f32_16x16x32_bf16 v[84:87], v[160:163], v[196:199], v[84:87]
	v_mfma_f32_16x16x32_bf16 v[80:83], v[172:175], v[196:199], v[80:83]
	v_mfma_f32_16x16x32_bf16 v[68:71], v[160:163], v[204:207], v[68:71]
	v_mfma_f32_16x16x32_bf16 v[64:67], v[172:175], v[204:207], v[64:67]
	s_setprio 0
	s_barrier
	s_add_i32 s40, s42, s33
	s_mov_b32 m0, s40
	ds_read_b128 v[176:179], v164 offset:49152
	ds_read_b128 v[180:183], v164 offset:50176
	ds_read_b128 v[184:187], v164 offset:51200
	ds_read_b128 v[188:191], v164 offset:52224
	ds_read_b128 v[192:195], v164 offset:53248
	ds_read_b128 v[196:199], v164 offset:54272
	ds_read_b128 v[200:203], v164 offset:55296
	ds_read_b128 v[204:207], v164 offset:56320
	global_load_lds_dwordx4 v166, s[36:37]
	s_add_i32 m0, s40, 0x2000
	s_nop 0
	global_load_lds_dwordx4 v134, s[36:37]
	s_add_i32 s36, s43, s33
	s_mov_b32 m0, s36
	s_nop 0
	global_load_lds_dwordx4 v166, s[28:29]
	s_add_i32 m0, s36, 0x2000
	s_nop 0
	global_load_lds_dwordx4 v134, s[28:29]
	s_mov_b32 m0, s14
	s_nop 0
	global_load_lds_dwordx4 v128, s[34:35]
	s_mov_b32 m0, s15
	s_nop 0
	global_load_lds_dwordx4 v132, s[34:35]
	s_waitcnt vmcnt(9)
	s_waitcnt lgkmcnt(0)
	s_barrier
	s_setprio 1
	s_waitcnt lgkmcnt(0)
	v_mfma_f32_16x16x32_bf16 v[60:63], v[140:143], v[176:179], v[60:63]
	v_mfma_f32_16x16x32_bf16 v[56:59], v[148:151], v[176:179], v[56:59]
	v_mfma_f32_16x16x32_bf16 v[44:47], v[140:143], v[184:187], v[44:47]
	v_mfma_f32_16x16x32_bf16 v[40:43], v[148:151], v[184:187], v[40:43]
	v_mfma_f32_16x16x32_bf16 v[28:31], v[140:143], v[192:195], v[28:31]
	v_mfma_f32_16x16x32_bf16 v[24:27], v[148:151], v[192:195], v[24:27]
	v_mfma_f32_16x16x32_bf16 v[12:15], v[140:143], v[200:203], v[12:15]
	v_mfma_f32_16x16x32_bf16 v[8:11], v[148:151], v[200:203], v[8:11]
	v_mfma_f32_16x16x32_bf16 v[60:63], v[144:147], v[180:183], v[60:63]
	v_mfma_f32_16x16x32_bf16 v[56:59], v[152:155], v[180:183], v[56:59]
	v_mfma_f32_16x16x32_bf16 v[44:47], v[144:147], v[188:191], v[44:47]
	v_mfma_f32_16x16x32_bf16 v[40:43], v[152:155], v[188:191], v[40:43]
	v_mfma_f32_16x16x32_bf16 v[28:31], v[144:147], v[196:199], v[28:31]
	v_mfma_f32_16x16x32_bf16 v[24:27], v[152:155], v[196:199], v[24:27]
	v_mfma_f32_16x16x32_bf16 v[12:15], v[144:147], v[204:207], v[12:15]
	v_mfma_f32_16x16x32_bf16 v[8:11], v[152:155], v[204:207], v[8:11]
	s_setprio 0
	s_setprio 1
	v_mfma_f32_16x16x32_bf16 v[52:55], v[156:159], v[176:179], v[52:55]
	v_mfma_f32_16x16x32_bf16 v[48:51], v[168:171], v[176:179], v[48:51]
	v_mfma_f32_16x16x32_bf16 v[36:39], v[156:159], v[184:187], v[36:39]
	v_mfma_f32_16x16x32_bf16 v[32:35], v[168:171], v[184:187], v[32:35]
	v_mfma_f32_16x16x32_bf16 v[20:23], v[156:159], v[192:195], v[20:23]
	v_mfma_f32_16x16x32_bf16 v[16:19], v[168:171], v[192:195], v[16:19]
	v_mfma_f32_16x16x32_bf16 v[4:7], v[156:159], v[200:203], v[4:7]
	v_mfma_f32_16x16x32_bf16 v[0:3], v[168:171], v[200:203], v[0:3]
	v_mfma_f32_16x16x32_bf16 v[52:55], v[160:163], v[180:183], v[52:55]
	v_mfma_f32_16x16x32_bf16 v[48:51], v[172:175], v[180:183], v[48:51]
	v_mfma_f32_16x16x32_bf16 v[36:39], v[160:163], v[188:191], v[36:39]
	v_mfma_f32_16x16x32_bf16 v[32:35], v[172:175], v[188:191], v[32:35]
	v_mfma_f32_16x16x32_bf16 v[20:23], v[160:163], v[196:199], v[20:23]
	v_mfma_f32_16x16x32_bf16 v[16:19], v[172:175], v[196:199], v[16:19]
	v_mfma_f32_16x16x32_bf16 v[4:7], v[160:163], v[204:207], v[4:7]
	v_mfma_f32_16x16x32_bf16 v[0:3], v[172:175], v[204:207], v[0:3]
	s_setprio 0
	s_barrier
	s_add_i32 s67, s67, 2
	s_add_u32 s61, s61, 0x100
	s_addc_u32 s66, s66, 0
	s_cmp_gt_u32 s67, 29
	s_mov_b64 s[28:29], s[30:31]
.LBB0_182:
	s_add_u32 s30, s28, 0x100
	s_addc_u32 s31, s29, 0
	s_cmp_eq_u32 s67, 28
	s_cselect_b32 s42, s7, s30
	s_cselect_b32 s43, s5, s31
	s_cselect_b32 s45, s19, s66
	s_cselect_b32 s44, s21, s61
	s_add_u32 s34, s42, 0x80
	s_addc_u32 s35, s43, 0
	s_add_u32 s36, s44, 0x80
	s_addc_u32 s37, s45, 0
	s_add_u32 s68, s28, 0x80080
	s_addc_u32 s69, s29, 0
	s_add_u32 s40, s42, 0x80000
	s_addc_u32 s41, s43, 0
	s_add_u32 s46, s44, 0x80000
	s_addc_u32 s47, s45, 0
	s_add_u32 s28, s44, 0x80080
	s_addc_u32 s29, s45, 0
	ds_read_b128 v[140:143], v133
	ds_read_b128 v[144:147], v133 offset:1024
	ds_read_b128 v[148:151], v133 offset:2048
	ds_read_b128 v[152:155], v133 offset:3072
	ds_read_b128 v[156:159], v135
	ds_read_b128 v[160:163], v135 offset:1024
	ds_read_b128 v[168:171], v135 offset:2048
	ds_read_b128 v[172:175], v135 offset:3072
	s_add_i32 m0, s38, 0xc000
	ds_read_b128 v[176:179], v164
	ds_read_b128 v[180:183], v164 offset:1024
	ds_read_b128 v[184:187], v164 offset:2048
	ds_read_b128 v[188:191], v164 offset:3072
	ds_read_b128 v[192:195], v164 offset:4096
	ds_read_b128 v[196:199], v164 offset:5120
	ds_read_b128 v[200:203], v164 offset:6144
	ds_read_b128 v[204:207], v164 offset:7168
	global_load_lds_dwordx4 v128, s[68:69]
	s_add_i32 m0, s38, 0xe000
	s_nop 0
	global_load_lds_dwordx4 v132, s[68:69]
	s_waitcnt vmcnt(8)
	s_waitcnt lgkmcnt(0)
	s_barrier
	s_setprio 1
	s_waitcnt lgkmcnt(0)
	v_mfma_f32_16x16x32_bf16 v[124:127], v[140:143], v[176:179], v[124:127]
	v_mov_b32_e32 v208, v210
	v_mfma_f32_16x16x32_bf16 v[120:123], v[148:151], v[176:179], v[120:123]
	v_mov_b32_e32 v209, v211
	v_mfma_f32_16x16x32_bf16 v[108:111], v[140:143], v[184:187], v[108:111]
	v_mov_b32_e32 v210, v212
	v_mfma_f32_16x16x32_bf16 v[104:107], v[148:151], v[184:187], v[104:107]
	v_mov_b32_e32 v211, v213
	v_mfma_f32_16x16x32_bf16 v[92:95], v[140:143], v[192:195], v[92:95]
	v_mov_b32_e32 v212, v214
	v_mfma_f32_16x16x32_bf16 v[88:91], v[148:151], v[192:195], v[88:91]
	v_mov_b32_e32 v213, v215
	v_mfma_f32_16x16x32_bf16 v[76:79], v[140:143], v[200:203], v[76:79]
	v_mov_b32_e32 v214, v216
	v_mfma_f32_16x16x32_bf16 v[72:75], v[148:151], v[200:203], v[72:75]
	v_mov_b32_e32 v215, v217
	v_mfma_f32_16x16x32_bf16 v[124:127], v[144:147], v[180:183], v[124:127]
	v_mov_b32_e32 v216, v218
	v_mfma_f32_16x16x32_bf16 v[120:123], v[152:155], v[180:183], v[120:123]
	v_mov_b32_e32 v217, v219
	v_mfma_f32_16x16x32_bf16 v[108:111], v[144:147], v[188:191], v[108:111]
	v_mov_b32_e32 v218, v220
	v_mfma_f32_16x16x32_bf16 v[104:107], v[152:155], v[188:191], v[104:107]
	v_mov_b32_e32 v219, v221
	v_mfma_f32_16x16x32_bf16 v[92:95], v[144:147], v[196:199], v[92:95]
	v_mov_b32_e32 v220, v222
	v_mfma_f32_16x16x32_bf16 v[88:91], v[152:155], v[196:199], v[88:91]
	v_mov_b32_e32 v221, v223
	v_mfma_f32_16x16x32_bf16 v[76:79], v[144:147], v[204:207], v[76:79]
	v_mov_b32_e32 v222, v224
	v_mfma_f32_16x16x32_bf16 v[72:75], v[152:155], v[204:207], v[72:75]
	v_mov_b32_e32 v223, v225
	s_setprio 0
	s_setprio 1
	v_mfma_f32_16x16x32_bf16 v[116:119], v[156:159], v[176:179], v[116:119]
	v_mov_b32_e32 v224, v226
	v_mfma_f32_16x16x32_bf16 v[112:115], v[168:171], v[176:179], v[112:115]
	v_mov_b32_e32 v225, v227
	v_mfma_f32_16x16x32_bf16 v[100:103], v[156:159], v[184:187], v[100:103]
	v_mov_b32_e32 v226, v228
	v_mfma_f32_16x16x32_bf16 v[96:99], v[168:171], v[184:187], v[96:99]
	v_mov_b32_e32 v227, v229
	v_mfma_f32_16x16x32_bf16 v[84:87], v[156:159], v[192:195], v[84:87]
	v_mov_b32_e32 v228, v230
	v_mfma_f32_16x16x32_bf16 v[80:83], v[168:171], v[192:195], v[80:83]
	v_mov_b32_e32 v229, v231
	v_mfma_f32_16x16x32_bf16 v[68:71], v[156:159], v[200:203], v[68:71]
	v_mov_b32_e32 v230, v232
	v_mfma_f32_16x16x32_bf16 v[64:67], v[168:171], v[200:203], v[64:67]
	v_mov_b32_e32 v231, v233
	v_mfma_f32_16x16x32_bf16 v[116:119], v[160:163], v[180:183], v[116:119]
	v_mov_b32_e32 v232, v234
	v_mfma_f32_16x16x32_bf16 v[112:115], v[172:175], v[180:183], v[112:115]
	v_mov_b32_e32 v233, v235
	v_mfma_f32_16x16x32_bf16 v[100:103], v[160:163], v[188:191], v[100:103]
	v_mov_b32_e32 v234, v236
	v_mfma_f32_16x16x32_bf16 v[96:99], v[172:175], v[188:191], v[96:99]
	v_mov_b32_e32 v235, v237
	v_mfma_f32_16x16x32_bf16 v[84:87], v[160:163], v[196:199], v[84:87]
	v_mov_b32_e32 v236, v238
	v_mfma_f32_16x16x32_bf16 v[80:83], v[172:175], v[196:199], v[80:83]
	v_mov_b32_e32 v237, v239
	v_mfma_f32_16x16x32_bf16 v[68:71], v[160:163], v[204:207], v[68:71]
	v_mfma_f32_16x16x32_bf16 v[64:67], v[172:175], v[204:207], v[64:67]
	s_setprio 0
	s_barrier
	s_add_i32 s68, s57, s33
	s_mov_b32 m0, s68
	ds_read_b128 v[176:179], v164 offset:16384
	ds_read_b128 v[180:183], v164 offset:17408
	ds_read_b128 v[184:187], v164 offset:18432
	ds_read_b128 v[188:191], v164 offset:19456
	ds_read_b128 v[192:195], v164 offset:20480
	ds_read_b128 v[196:199], v164 offset:21504
	ds_read_b128 v[200:203], v164 offset:22528
	ds_read_b128 v[204:207], v164 offset:23552
	global_load_lds_dwordx4 v166, s[44:45]
	s_add_i32 m0, s68, 0x2000
	s_nop 0
	global_load_lds_dwordx4 v134, s[44:45]
	s_add_i32 s44, s60, s33
	s_mov_b32 m0, s44
	s_nop 0
	global_load_lds_dwordx4 v166, s[46:47]
	s_add_i32 m0, s44, 0x2000
	s_nop 0
	global_load_lds_dwordx4 v134, s[46:47]
	s_mov_b32 m0, s38
	s_nop 0
	global_load_lds_dwordx4 v128, s[42:43]
	s_mov_b32 m0, s39
	s_nop 0
	global_load_lds_dwordx4 v132, s[42:43]
	global_load_dwordx2 v[238:239], v250, s[98:99] nt
	s_add_u32 s98, s98, 0x2000
	s_addc_u32 s99, s99, 0
	s_waitcnt vmcnt(9)
	s_waitcnt lgkmcnt(0)
	s_barrier
	s_setprio 1
	s_waitcnt lgkmcnt(0)
	v_mfma_f32_16x16x32_bf16 v[60:63], v[140:143], v[176:179], v[60:63]
	v_mfma_f32_16x16x32_bf16 v[56:59], v[148:151], v[176:179], v[56:59]
	v_mfma_f32_16x16x32_bf16 v[44:47], v[140:143], v[184:187], v[44:47]
	v_mfma_f32_16x16x32_bf16 v[40:43], v[148:151], v[184:187], v[40:43]
	v_mfma_f32_16x16x32_bf16 v[28:31], v[140:143], v[192:195], v[28:31]
	v_mfma_f32_16x16x32_bf16 v[24:27], v[148:151], v[192:195], v[24:27]
	v_mfma_f32_16x16x32_bf16 v[12:15], v[140:143], v[200:203], v[12:15]
	v_mfma_f32_16x16x32_bf16 v[8:11], v[148:151], v[200:203], v[8:11]
	v_mfma_f32_16x16x32_bf16 v[60:63], v[144:147], v[180:183], v[60:63]
	v_mfma_f32_16x16x32_bf16 v[56:59], v[152:155], v[180:183], v[56:59]
	v_mfma_f32_16x16x32_bf16 v[44:47], v[144:147], v[188:191], v[44:47]
	v_mfma_f32_16x16x32_bf16 v[40:43], v[152:155], v[188:191], v[40:43]
	v_mfma_f32_16x16x32_bf16 v[28:31], v[144:147], v[196:199], v[28:31]
	v_mfma_f32_16x16x32_bf16 v[24:27], v[152:155], v[196:199], v[24:27]
	v_mfma_f32_16x16x32_bf16 v[12:15], v[144:147], v[204:207], v[12:15]
	v_mfma_f32_16x16x32_bf16 v[8:11], v[152:155], v[204:207], v[8:11]
	s_setprio 0
	s_setprio 1
	v_mfma_f32_16x16x32_bf16 v[52:55], v[156:159], v[176:179], v[52:55]
	v_mfma_f32_16x16x32_bf16 v[48:51], v[168:171], v[176:179], v[48:51]
	v_mfma_f32_16x16x32_bf16 v[36:39], v[156:159], v[184:187], v[36:39]
	v_mfma_f32_16x16x32_bf16 v[32:35], v[168:171], v[184:187], v[32:35]
	v_mfma_f32_16x16x32_bf16 v[20:23], v[156:159], v[192:195], v[20:23]
	v_mfma_f32_16x16x32_bf16 v[16:19], v[168:171], v[192:195], v[16:19]
	v_mfma_f32_16x16x32_bf16 v[4:7], v[156:159], v[200:203], v[4:7]
	v_mfma_f32_16x16x32_bf16 v[0:3], v[168:171], v[200:203], v[0:3]
	v_mfma_f32_16x16x32_bf16 v[52:55], v[160:163], v[180:183], v[52:55]
	v_mfma_f32_16x16x32_bf16 v[48:51], v[172:175], v[180:183], v[48:51]
	v_mfma_f32_16x16x32_bf16 v[36:39], v[160:163], v[188:191], v[36:39]
	v_mfma_f32_16x16x32_bf16 v[32:35], v[172:175], v[188:191], v[32:35]
	v_mfma_f32_16x16x32_bf16 v[20:23], v[160:163], v[196:199], v[20:23]
	v_mfma_f32_16x16x32_bf16 v[16:19], v[172:175], v[196:199], v[16:19]
	v_mfma_f32_16x16x32_bf16 v[4:7], v[160:163], v[204:207], v[4:7]
	v_mfma_f32_16x16x32_bf16 v[0:3], v[172:175], v[204:207], v[0:3]
	s_setprio 0
	s_barrier
	s_add_i32 s42, 0, 0x18000
	v_add_u32_e32 v130, s42, v129
	s_add_i32 s43, 0, 0x1c000
	ds_read_b128 v[140:143], v130
	ds_read_b128 v[144:147], v130 offset:1024
	ds_read_b128 v[148:151], v130 offset:2048
	ds_read_b128 v[152:155], v130 offset:3072
	v_add_u32_e32 v130, s43, v129
	ds_read_b128 v[156:159], v130
	ds_read_b128 v[160:163], v130 offset:1024
	ds_read_b128 v[168:171], v130 offset:2048
	ds_read_b128 v[172:175], v130 offset:3072
	s_mov_b32 m0, s52
	ds_read_b128 v[176:179], v164 offset:32768
	ds_read_b128 v[180:183], v164 offset:33792
	ds_read_b128 v[184:187], v164 offset:34816
	ds_read_b128 v[188:191], v164 offset:35840
	ds_read_b128 v[192:195], v164 offset:36864
	ds_read_b128 v[196:199], v164 offset:37888
	ds_read_b128 v[200:203], v164 offset:38912
	ds_read_b128 v[204:207], v164 offset:39936
	global_load_lds_dwordx4 v128, s[40:41]
	s_mov_b32 m0, s53
	s_nop 0
	global_load_lds_dwordx4 v132, s[40:41]
	s_waitcnt vmcnt(9)
	s_waitcnt lgkmcnt(0)
	s_barrier
	s_setprio 1
	s_waitcnt lgkmcnt(0)
	v_mfma_f32_16x16x32_bf16 v[124:127], v[140:143], v[176:179], v[124:127]
	v_mfma_f32_16x16x32_bf16 v[120:123], v[148:151], v[176:179], v[120:123]
	v_mfma_f32_16x16x32_bf16 v[108:111], v[140:143], v[184:187], v[108:111]
	v_mfma_f32_16x16x32_bf16 v[104:107], v[148:151], v[184:187], v[104:107]
	v_mfma_f32_16x16x32_bf16 v[92:95], v[140:143], v[192:195], v[92:95]
	v_mfma_f32_16x16x32_bf16 v[88:91], v[148:151], v[192:195], v[88:91]
	v_mfma_f32_16x16x32_bf16 v[76:79], v[140:143], v[200:203], v[76:79]
	v_mfma_f32_16x16x32_bf16 v[72:75], v[148:151], v[200:203], v[72:75]
	v_mfma_f32_16x16x32_bf16 v[124:127], v[144:147], v[180:183], v[124:127]
	v_mfma_f32_16x16x32_bf16 v[120:123], v[152:155], v[180:183], v[120:123]
	v_mfma_f32_16x16x32_bf16 v[108:111], v[144:147], v[188:191], v[108:111]
	v_mfma_f32_16x16x32_bf16 v[104:107], v[152:155], v[188:191], v[104:107]
	v_mfma_f32_16x16x32_bf16 v[92:95], v[144:147], v[196:199], v[92:95]
	v_mfma_f32_16x16x32_bf16 v[88:91], v[152:155], v[196:199], v[88:91]
	v_mfma_f32_16x16x32_bf16 v[76:79], v[144:147], v[204:207], v[76:79]
	v_mfma_f32_16x16x32_bf16 v[72:75], v[152:155], v[204:207], v[72:75]
	s_setprio 0
	s_setprio 1
	v_mfma_f32_16x16x32_bf16 v[116:119], v[156:159], v[176:179], v[116:119]
	v_mfma_f32_16x16x32_bf16 v[112:115], v[168:171], v[176:179], v[112:115]
	v_mfma_f32_16x16x32_bf16 v[100:103], v[156:159], v[184:187], v[100:103]
	v_mfma_f32_16x16x32_bf16 v[96:99], v[168:171], v[184:187], v[96:99]
	v_mfma_f32_16x16x32_bf16 v[84:87], v[156:159], v[192:195], v[84:87]
	v_mfma_f32_16x16x32_bf16 v[80:83], v[168:171], v[192:195], v[80:83]
	v_mfma_f32_16x16x32_bf16 v[68:71], v[156:159], v[200:203], v[68:71]
	v_mfma_f32_16x16x32_bf16 v[64:67], v[168:171], v[200:203], v[64:67]
	v_mfma_f32_16x16x32_bf16 v[116:119], v[160:163], v[180:183], v[116:119]
	v_mfma_f32_16x16x32_bf16 v[112:115], v[172:175], v[180:183], v[112:115]
	v_mfma_f32_16x16x32_bf16 v[100:103], v[160:163], v[188:191], v[100:103]
	v_mfma_f32_16x16x32_bf16 v[96:99], v[172:175], v[188:191], v[96:99]
	v_mfma_f32_16x16x32_bf16 v[84:87], v[160:163], v[196:199], v[84:87]
	v_mfma_f32_16x16x32_bf16 v[80:83], v[172:175], v[196:199], v[80:83]
	v_mfma_f32_16x16x32_bf16 v[68:71], v[160:163], v[204:207], v[68:71]
	v_mfma_f32_16x16x32_bf16 v[64:67], v[172:175], v[204:207], v[64:67]
	s_setprio 0
	s_barrier
; #define PG8_MMA(ai, bj, At, Bt) do { __builtin_amdgcn_s_setprio(1); _Pragma("unroll") for (int m = 0; m < 4; ++m) _Pragma("unroll") for (int n = 0; n < 2; ++n) _Pragma("unroll") for (int k = 0; k < 2; ++k) \
;         acc[ai][bj][m][n] = __builtin_amdgcn_mfma_f32_16x16x32_bf16(Bt[n][k], At[m][k], acc[ai][bj][m][n], 0, 0, 0); __builtin_amdgcn_s_setprio(0); } while (0)
; #define PG8_MMA8(ai, bj, At, Bt) do { __builtin_amdgcn_s_setprio(1); _Pragma("unroll") for (int m = 0; m < 4; ++m) _Pragma("unroll") for (int n = 0; n < 2; ++n) \
;         acc[ai][bj][m][n] = __builtin_amdgcn_mfma_scale_f32_16x16x128_f8f6f4(PG8_CAT(Bt[n][0], Bt[n][1]), PG8_CAT(At[m][0], At[m][1]), acc[ai][bj][m][n], 0, 0, 0, 0, 0, 0); __builtin_amdgcn_s_setprio(0); } while (0)
; #define PG8_BAR __builtin_amdgcn_s_barrier()
;     ...
;         { const int tmid = (TSW > 0 && TSW < nt) ? TSW : nt;
;           _Pragma("unroll 1") for (int t = 0; t < tmid; t += 2) { PG8_BODY(PG8_MMA) }
;           if constexpr (TSW > 0) { _Pragma("unroll 1") for (int t = tmid; t < nt; t += 2) { PG8_BODY(PG8_MMA8) } } }
;     ...
;         if constexpr (ALIGN_EPI) { if (wr == 0) PG8_BAR; }
	s_add_i32 s40, s42, s33
	s_mov_b32 m0, s40
	ds_read_b128 v[176:179], v164 offset:49152
	ds_read_b128 v[180:183], v164 offset:50176
	ds_read_b128 v[184:187], v164 offset:51200
	ds_read_b128 v[188:191], v164 offset:52224
	ds_read_b128 v[192:195], v164 offset:53248
	ds_read_b128 v[196:199], v164 offset:54272
	ds_read_b128 v[200:203], v164 offset:55296
	ds_read_b128 v[204:207], v164 offset:56320
	global_load_lds_dwordx4 v166, s[36:37]
	s_add_i32 m0, s40, 0x2000
	s_nop 0
	global_load_lds_dwordx4 v134, s[36:37]
	s_add_i32 s36, s43, s33
	s_mov_b32 m0, s36
	s_nop 0
	global_load_lds_dwordx4 v166, s[28:29]
	s_add_i32 m0, s36, 0x2000
	s_nop 0
	global_load_lds_dwordx4 v134, s[28:29]
	s_mov_b32 m0, s14
	s_nop 0
	global_load_lds_dwordx4 v128, s[34:35]
	s_mov_b32 m0, s15
	s_nop 0
	global_load_lds_dwordx4 v132, s[34:35]
	s_waitcnt vmcnt(9)
	s_waitcnt lgkmcnt(0)
	s_barrier
	s_setprio 1
	s_waitcnt lgkmcnt(0)
	v_mfma_f32_16x16x32_bf16 v[60:63], v[140:143], v[176:179], v[60:63]
	v_mfma_f32_16x16x32_bf16 v[56:59], v[148:151], v[176:179], v[56:59]
	v_mfma_f32_16x16x32_bf16 v[44:47], v[140:143], v[184:187], v[44:47]
	v_mfma_f32_16x16x32_bf16 v[40:43], v[148:151], v[184:187], v[40:43]
	v_mfma_f32_16x16x32_bf16 v[28:31], v[140:143], v[192:195], v[28:31]
	v_mfma_f32_16x16x32_bf16 v[24:27], v[148:151], v[192:195], v[24:27]
	v_mfma_f32_16x16x32_bf16 v[12:15], v[140:143], v[200:203], v[12:15]
	v_mfma_f32_16x16x32_bf16 v[8:11], v[148:151], v[200:203], v[8:11]
	v_mfma_f32_16x16x32_bf16 v[60:63], v[144:147], v[180:183], v[60:63]
	v_mfma_f32_16x16x32_bf16 v[56:59], v[152:155], v[180:183], v[56:59]
	v_mfma_f32_16x16x32_bf16 v[44:47], v[144:147], v[188:191], v[44:47]
	v_mfma_f32_16x16x32_bf16 v[40:43], v[152:155], v[188:191], v[40:43]
	v_mfma_f32_16x16x32_bf16 v[28:31], v[144:147], v[196:199], v[28:31]
	v_mfma_f32_16x16x32_bf16 v[24:27], v[152:155], v[196:199], v[24:27]
	v_mfma_f32_16x16x32_bf16 v[12:15], v[144:147], v[204:207], v[12:15]
	v_mfma_f32_16x16x32_bf16 v[8:11], v[152:155], v[204:207], v[8:11]
	s_setprio 0
	s_setprio 1
	v_mfma_f32_16x16x32_bf16 v[52:55], v[156:159], v[176:179], v[52:55]
	v_mfma_f32_16x16x32_bf16 v[48:51], v[168:171], v[176:179], v[48:51]
	v_mfma_f32_16x16x32_bf16 v[36:39], v[156:159], v[184:187], v[36:39]
	v_mfma_f32_16x16x32_bf16 v[32:35], v[168:171], v[184:187], v[32:35]
	v_mfma_f32_16x16x32_bf16 v[20:23], v[156:159], v[192:195], v[20:23]
	v_mfma_f32_16x16x32_bf16 v[16:19], v[168:171], v[192:195], v[16:19]
	v_mfma_f32_16x16x32_bf16 v[4:7], v[156:159], v[200:203], v[4:7]
	v_mfma_f32_16x16x32_bf16 v[0:3], v[168:171], v[200:203], v[0:3]
	v_mfma_f32_16x16x32_bf16 v[52:55], v[160:163], v[180:183], v[52:55]
	v_mfma_f32_16x16x32_bf16 v[48:51], v[172:175], v[180:183], v[48:51]
	v_mfma_f32_16x16x32_bf16 v[36:39], v[160:163], v[188:191], v[36:39]
	v_mfma_f32_16x16x32_bf16 v[32:35], v[172:175], v[188:191], v[32:35]
	v_mfma_f32_16x16x32_bf16 v[20:23], v[160:163], v[196:199], v[20:23]
	v_mfma_f32_16x16x32_bf16 v[16:19], v[172:175], v[196:199], v[16:19]
	v_mfma_f32_16x16x32_bf16 v[4:7], v[160:163], v[204:207], v[4:7]
	v_mfma_f32_16x16x32_bf16 v[0:3], v[172:175], v[204:207], v[0:3]
	s_setprio 0
	s_barrier
	s_add_i32 s67, s67, 2
	s_add_u32 s61, s61, 0x100
	s_addc_u32 s66, s66, 0
	s_cmp_gt_u32 s67, 29
	s_mov_b64 s[28:29], s[30:31]
	s_cbranch_scc0 .LBB0_182
	s_and_b64 vcc, exec, s[16:17]
	s_cbranch_vccz .LBB0_185
	s_barrier
;     __device__ __forceinline__ void operator()(const f32x4 (&acc)[2][2][4][2], const Unit& u, int wr, int wc, int fr, int fq) const {
;         { int l_ = (int)lane_id_fresh(); asm volatile("" : "+v"(l_)); fr = l_ & 15; fq = l_ >> 4; }
;         const int row0 = u.pm * BM + wr * 64 + fr; int colt = u.pn * BM; bf16_t* base = O;
;         float sc = 1.f; bool hm = false, k8 = false; if (split_cols) { const int t = colt / split_cols; base += (size_t)t * split_stride; colt -= t * split_cols; if (t == 0) sc = scale0; hm = HM && t < 3; k8 = HM && (t == 1 || t == 2); }
;         const int col0 = colt + wc * 32 + 8 * fq, gcol0 = u.pn * BM + wc * 32 + 8 * fq;
;         const size_t bstep = hm ? (size_t)4096 * 128 : (size_t)HALF;
;         f32x4 cv[2][2];
; #pragma unroll
;         for (int bj = 0; bj < 2; ++bj)
; #pragma unroll
;             for (int n = 0; n < 2; ++n) cv[bj][n] = CS ? *(const f32x4*)(cs + gcol0 + bj * HALF + 4 * n) : (f32x4){1.f, 1.f, 1.f, 1.f};
;         float rsv[2][4];
; #pragma unroll
;         for (int ai = 0; ai < 2; ++ai)
; #pragma unroll
;             for (int m = 0; m < 4; ++m) rsv[ai][m] = RS ? rs[row0 + ai * HALF + m * 16] : 1.0f;
; __device__ __forceinline__ void p0_transpose_item(const float* W, int ldw, int col_off, int K, int N, const float* rs, bf16_t* WT, LAS float* scr, int item, int lane) {
;     const int nblk = N / 32, kb = item / nblk, nb = item % nblk, k0 = 64 * kb, n0 = 32 * nb;
;     const int r8 = lane >> 3, c4 = (lane & 7) * 4;
;     f32x4 v[8]; float sc[8];
; #pragma unroll
;     for (int i = 0; i < 8; ++i) { const int kk = 8 * i + r8; v[i] = __builtin_nontemporal_load((const GAS f32x4*)(W + (size_t)(k0 + kk) * ldw + col_off + n0 + c4)); sc[i] = rs ? rs[k0 + kk] : 1.0f; }
; #pragma unroll
;     for (int i = 0; i < 8; ++i) { LAS float* d = scr + (8 * i + r8) * 33 + c4; d[0] = v[i].x * sc[i]; d[1] = v[i].y * sc[i]; d[2] = v[i].z * sc[i]; d[3] = v[i].w * sc[i]; }
;     LDS_WAIT();
;     const int c = lane & 7;
; #pragma unroll
;     for (int j = 0; j < 4; ++j) { const int n = (lane >> 3) + 8 * j; const LAS float* s = scr + (8 * c) * 33 + n;
;         v4u o; o.x = pk2(s[0 * 33], s[1 * 33]); o.y = pk2(s[2 * 33], s[3 * 33]); o.z = pk2(s[4 * 33], s[5 * 33]); o.w = pk2(s[6 * 33], s[7 * 33]);
;         *(GAS v4u*)(WT + (size_t)(n0 + n) * K + k0 + 8 * c) = o; }
;     LDS_WAIT();
; }
.LBB0_185:
	s_waitcnt vmcnt(8)
	v_readlane_b32 s98, v252, 5
	s_sub_i32 s99, s54, 1
	s_lshl_b32 s99, s99, 11
	s_add_i32 s98, s98, s99
	s_and_b32 s98, s98, 0x1fff
	s_lshr_b32 s99, s98, 6
	s_and_b32 s98, s98, 63
	s_lshl_b32 s98, s98, 19
	s_lshl_b32 s99, s99, 7
	s_add_u32 s98, s98, s99
	v_readlane_b32 s100, v252, 2
	v_readlane_b32 s101, v252, 3
	s_add_u32 s100, s100, s98
	s_addc_u32 s101, s101, 0
	v_mbcnt_lo_u32_b32 v249, -1, 0
	v_mbcnt_hi_u32_b32 v249, -1, v249
	v_lshrrev_b32_e32 v248, 4, v249
	v_and_b32_e32 v249, 15, v249
	v_lshlrev_b32_e32 v248, 5, v248
	v_lshl_or_b32 v248, v249, 15, v248
	v_add_u32_e32 v249, 0x4000, v248
	v_cvt_pk_bf16_f32 v208, v208, v210
	v_cvt_pk_bf16_f32 v209, v209, v211
	v_cvt_pk_bf16_f32 v210, v212, v214
	v_cvt_pk_bf16_f32 v211, v213, v215
	v_cvt_pk_bf16_f32 v212, v216, v218
	v_cvt_pk_bf16_f32 v213, v217, v219
	v_cvt_pk_bf16_f32 v214, v220, v222
	v_cvt_pk_bf16_f32 v215, v221, v223
	v_cvt_pk_bf16_f32 v216, v224, v226
	v_cvt_pk_bf16_f32 v217, v225, v227
	v_cvt_pk_bf16_f32 v218, v228, v230
	v_cvt_pk_bf16_f32 v219, v229, v231
	v_cvt_pk_bf16_f32 v220, v232, v234
	v_cvt_pk_bf16_f32 v221, v233, v235
	v_cvt_pk_bf16_f32 v222, v236, v238
	v_cvt_pk_bf16_f32 v223, v237, v239
	v_mov_b32_e32 v224, v208
	v_mov_b32_e32 v232, v209
	v_mov_b32_e32 v225, v210
	v_mov_b32_e32 v233, v211
	v_mov_b32_e32 v226, v212
	v_mov_b32_e32 v234, v213
	v_mov_b32_e32 v227, v214
	v_mov_b32_e32 v235, v215
	v_mov_b32_e32 v228, v216
	v_mov_b32_e32 v236, v217
	v_mov_b32_e32 v229, v218
	v_mov_b32_e32 v237, v219
	v_mov_b32_e32 v230, v220
	v_mov_b32_e32 v238, v221
	v_mov_b32_e32 v231, v222
	v_mov_b32_e32 v239, v223
	global_store_dwordx4 v248, v[224:227], s[100:101]
	global_store_dwordx4 v248, v[228:231], s[100:101] offset:16
	global_store_dwordx4 v249, v[232:235], s[100:101]
	global_store_dwordx4 v249, v[236:239], s[100:101] offset:16
	s_mov_b32 s5, -1
	s_lshl_b32 s19, s4, 8
	v_mbcnt_lo_u32_b32 v130, s5, 0
	v_mbcnt_hi_u32_b32 v130, s5, v130
	s_lshl_b32 s5, s6, 8
	s_add_i32 s5, s5, s48
	s_ashr_i32 s6, s4, 31
	v_and_or_b32 v140, v130, 15, s5
	v_ashrrev_i32_e32 v141, 31, v140
	v_or_b32_e32 v152, 16, v140
	v_or_b32_e32 v150, 32, v140
	v_or_b32_e32 v146, 48, v140
	v_lshl_add_u64 v[142:143], v[140:141], 2, s[12:13]
	v_ashrrev_i32_e32 v153, 31, v152
	v_ashrrev_i32_e32 v151, 31, v150
	v_ashrrev_i32_e32 v147, 31, v146
	v_lshl_add_u64 v[144:145], v[152:153], 2, s[12:13]
	v_lshl_add_u64 v[148:149], v[150:151], 2, s[12:13]
	v_lshl_add_u64 v[154:155], v[146:147], 2, s[12:13]
	v_mov_b32_e32 v158, v240
	v_mov_b32_e32 v173, v241
	v_mov_b32_e32 v172, v242
	v_mov_b32_e32 v171, v243
	v_mov_b32_e32 v170, v244
	v_mov_b32_e32 v169, v245
	v_mov_b32_e32 v168, v246
	v_mov_b32_e32 v167, v247
	s_lshl_b32 vcc_lo, s20, 8
	s_add_i32 vcc_lo, vcc_lo, s48
	s_cmp_lg_u64 s[8:9], 0
	s_cselect_b32 vcc_lo, vcc_lo, s5
	v_and_or_b32 v248, v140, 15, vcc_lo
	v_mov_b32_e32 v249, 0
	v_lshl_add_u64 v[248:249], v[248:249], 2, s[12:13]
	global_load_dword v240, v[248:249], off
	global_load_dword v241, v[248:249], off offset:64
	global_load_dword v242, v[248:249], off offset:128
	global_load_dword v243, v[248:249], off offset:192
	global_load_dword v244, v[248:249], off offset:512
	global_load_dword v245, v[248:249], off offset:576
	global_load_dword v246, v[248:249], off offset:640
	global_load_dword v247, v[248:249], off offset:704
	s_lshr_b32 s6, s6, 30
	s_add_i32 s6, s4, s6
	s_ashr_i32 s36, s6, 2
	s_ashr_i32 s37, s36, 31
	s_lshl_b64 s[6:7], s[36:37], 25
	s_add_u32 s28, s84, s6
	s_addc_u32 s29, s85, s7
	s_lshl_b32 s6, s36, 10
	s_sub_i32 s19, s19, s6
	s_cmp_lt_i32 s4, 12
	s_cselect_b64 s[6:7], -1, 0
	s_cmp_gt_i32 s4, 11
	v_ashrrev_i32_e32 v130, 1, v130
	s_cselect_b64 s[30:31], -1, 0
	v_and_b32_e32 v156, -8, v130
	s_or_b32 s21, s19, s50
	v_add_u32_e32 v142, s21, v156
	s_add_u32 s34, s28, s50
	s_addc_u32 s35, s29, 0
	v_ashrrev_i32_e32 v143, 31, v142
	v_lshl_add_u64 v[142:143], v[142:143], 1, s[28:29]
	s_add_u32 s28, s34, s50
	s_addc_u32 s29, s35, 0
	s_mov_b64 s[40:41], -1
	s_and_b64 vcc, exec, s[30:31]
	v_lshlrev_b32_e32 v159, 7, v140
	s_cbranch_vccz .LBB0_187
	v_lshlrev_b64 v[144:145], 11, v[140:141]
	v_lshl_add_u64 v[154:155], v[142:143], 0, v[144:145]
	v_and_b32_e32 v130, 0x7e780, v159
	s_mov_b64 s[40:41], 0
